# phase-7 GEMM loop: the 16 per-phase s_setprio flips deleted
# speedup vs baseline: 1.0062x; 1.0038x over previous
.LBB0_80:
	s_add_u32 s22, s52, 0xfffc0080
	s_addc_u32 s23, s53, -1
	s_add_i32 s24, 0, 0x10000
	v_add_u32_e32 v64, s24, v235
	ds_read_b128 v[52:55], v64
	ds_read_b128 v[56:59], v64 offset:1024
	ds_read_b128 v[60:63], v64 offset:2048
	ds_read_b128 v[64:67], v64 offset:3072
	s_cmp_eq_u32 s21, 12
	s_cselect_b32 s57, s47, s23
	s_cselect_b32 s56, s46, s22
	s_cselect_b32 s55, s49, s20
	s_cselect_b32 s54, s48, s1
	v_lshl_add_u64 v[116:117], s[52:53], 0, v[206:207]
	s_add_i32 m0, s62, 0xc000
	ds_read_b128 v[76:79], v239
	ds_read_b128 v[80:83], v239 offset:1024
	ds_read_b128 v[84:87], v239 offset:2048
	ds_read_b128 v[88:91], v239 offset:3072
	ds_read_b128 v[92:95], v239 offset:4096
	ds_read_b128 v[96:99], v239 offset:5120
	ds_read_b128 v[100:103], v239 offset:6144
	ds_read_b128 v[104:107], v239 offset:7168
	global_load_lds_dwordx4 v[116:117], off
	v_lshl_add_u64 v[116:117], s[52:53], 0, v[208:209]
	s_add_i32 m0, s62, 0xe000
	s_nop 0
	global_load_lds_dwordx4 v[116:117], off
	s_waitcnt lgkmcnt(8)
	s_barrier
	s_waitcnt lgkmcnt(0)
	s_waitcnt lgkmcnt(0)
	v_mfma_f32_16x16x32_bf16 v[160:163], v[52:55], v[92:95], v[160:163]
	v_mfma_f32_16x16x32_bf16 v[152:155], v[60:63], v[92:95], v[152:155]
	v_mfma_f32_16x16x32_bf16 v[144:147], v[52:55], v[100:103], v[144:147]
	v_mfma_f32_16x16x32_bf16 v[140:143], v[60:63], v[100:103], v[140:143]
	v_mfma_f32_16x16x32_bf16 v[116:119], v[52:55], v[76:79], v[192:195]
	v_mfma_f32_16x16x32_bf16 v[120:123], v[60:63], v[76:79], v[184:187]
	v_mfma_f32_16x16x32_bf16 v[124:127], v[52:55], v[84:87], v[176:179]
	v_mfma_f32_16x16x32_bf16 v[128:131], v[60:63], v[84:87], v[168:171]
	v_mfma_f32_16x16x32_bf16 v[160:163], v[56:59], v[96:99], v[160:163]
	v_mfma_f32_16x16x32_bf16 v[152:155], v[64:67], v[96:99], v[152:155]
	v_mfma_f32_16x16x32_bf16 v[144:147], v[56:59], v[104:107], v[144:147]
	v_mfma_f32_16x16x32_bf16 v[140:143], v[64:67], v[104:107], v[140:143]
	v_mfma_f32_16x16x32_bf16 v[116:119], v[56:59], v[80:83], v[116:119]
	v_mfma_f32_16x16x32_bf16 v[120:123], v[64:67], v[80:83], v[120:123]
	v_mfma_f32_16x16x32_bf16 v[124:127], v[56:59], v[88:91], v[124:127]
	v_mfma_f32_16x16x32_bf16 v[128:131], v[64:67], v[88:91], v[128:131]
	s_barrier
	s_add_i32 s25, 0, 0x14000
	s_add_i32 s22, s24, s60
	v_add_u32_e32 v192, s25, v235
	v_lshl_add_u64 v[198:199], s[54:55], 0, v[2:3]
	s_mov_b32 m0, s22
	ds_read_b128 v[168:171], v192
	ds_read_b128 v[176:179], v192 offset:1024
	ds_read_b128 v[184:187], v192 offset:2048
	ds_read_b128 v[192:195], v192 offset:3072
	global_load_lds_dwordx4 v[198:199], off
	v_lshl_add_u64 v[222:223], s[54:55], 0, v[0:1]
	s_add_i32 m0, s22, 0x2000
	s_nop 0
	global_load_lds_dwordx4 v[222:223], off
	s_barrier
	s_waitcnt lgkmcnt(0)
	s_waitcnt lgkmcnt(0)
	v_mfma_f32_16x16x32_bf16 v[188:191], v[168:171], v[76:79], v[188:191]
	v_mfma_f32_16x16x32_bf16 v[76:79], v[184:187], v[76:79], v[180:183]
	v_mfma_f32_16x16x32_bf16 v[188:191], v[176:179], v[80:83], v[188:191]
	v_mfma_f32_16x16x32_bf16 v[76:79], v[192:195], v[80:83], v[76:79]
	v_mfma_f32_16x16x32_bf16 v[80:83], v[168:171], v[84:87], v[172:175]
	v_mfma_f32_16x16x32_bf16 v[84:87], v[184:187], v[84:87], v[164:167]
	v_mfma_f32_16x16x32_bf16 v[80:83], v[176:179], v[88:91], v[80:83]
	v_mfma_f32_16x16x32_bf16 v[84:87], v[192:195], v[88:91], v[84:87]
	v_mfma_f32_16x16x32_bf16 v[88:91], v[168:171], v[92:95], v[156:159]
	v_mfma_f32_16x16x32_bf16 v[92:95], v[184:187], v[92:95], v[148:151]
	v_mfma_f32_16x16x32_bf16 v[88:91], v[176:179], v[96:99], v[88:91]
	v_mfma_f32_16x16x32_bf16 v[92:95], v[192:195], v[96:99], v[92:95]
	v_mfma_f32_16x16x32_bf16 v[96:99], v[168:171], v[100:103], v[136:139]
	v_mfma_f32_16x16x32_bf16 v[100:103], v[184:187], v[100:103], v[132:135]
	v_mfma_f32_16x16x32_bf16 v[96:99], v[176:179], v[104:107], v[96:99]
	v_mfma_f32_16x16x32_bf16 v[100:103], v[192:195], v[104:107], v[100:103]
	s_mov_b32 m0, s62
	v_lshl_add_u64 v[248:249], s[56:57], 0, v[204:205]
	s_barrier
	ds_read_b128 v[104:107], v239 offset:16384
	ds_read_b128 v[132:135], v239 offset:17408
	ds_read_b128 v[136:139], v239 offset:18432
	ds_read_b128 v[148:151], v239 offset:19456
	ds_read_b128 v[156:159], v239 offset:20480
	ds_read_b128 v[164:167], v239 offset:21504
	ds_read_b128 v[172:175], v239 offset:22528
	ds_read_b128 v[180:183], v239 offset:23552
	global_load_lds_dwordx4 v[248:249], off
	v_lshl_add_u64 v[250:251], s[56:57], 0, v[202:203]
	s_mov_b32 m0, s63
	s_nop 0
	global_load_lds_dwordx4 v[250:251], off
	s_barrier
	s_waitcnt lgkmcnt(0)
	s_waitcnt lgkmcnt(0)
	v_mfma_f32_16x16x32_bf16 v[112:115], v[52:55], v[104:107], v[112:115]
	v_mfma_f32_16x16x32_bf16 v[72:75], v[60:63], v[104:107], v[72:75]
	v_mfma_f32_16x16x32_bf16 v[48:51], v[52:55], v[136:139], v[48:51]
	v_mfma_f32_16x16x32_bf16 v[40:43], v[60:63], v[136:139], v[40:43]
	v_mfma_f32_16x16x32_bf16 v[32:35], v[52:55], v[156:159], v[32:35]
	v_mfma_f32_16x16x32_bf16 v[24:27], v[60:63], v[156:159], v[24:27]
	v_mfma_f32_16x16x32_bf16 v[16:19], v[52:55], v[172:175], v[16:19]
	v_mfma_f32_16x16x32_bf16 v[12:15], v[60:63], v[172:175], v[12:15]
	v_mfma_f32_16x16x32_bf16 v[112:115], v[56:59], v[132:135], v[112:115]
	v_mfma_f32_16x16x32_bf16 v[72:75], v[64:67], v[132:135], v[72:75]
	v_mfma_f32_16x16x32_bf16 v[48:51], v[56:59], v[148:151], v[48:51]
	v_mfma_f32_16x16x32_bf16 v[40:43], v[64:67], v[148:151], v[40:43]
	v_mfma_f32_16x16x32_bf16 v[32:35], v[56:59], v[164:167], v[32:35]
	v_mfma_f32_16x16x32_bf16 v[24:27], v[64:67], v[164:167], v[24:27]
	v_mfma_f32_16x16x32_bf16 v[16:19], v[56:59], v[180:183], v[16:19]
	v_mfma_f32_16x16x32_bf16 v[12:15], v[64:67], v[180:183], v[12:15]
	s_barrier
	s_add_u32 s22, s54, 0x40000
	s_addc_u32 s23, s55, 0
	s_add_i32 s24, s25, s60
	v_lshl_add_u64 v[52:53], s[22:23], 0, v[2:3]
	s_mov_b32 m0, s24
	s_nop 0
	global_load_lds_dwordx4 v[52:53], off
	v_lshl_add_u64 v[52:53], s[22:23], 0, v[0:1]
	s_add_i32 m0, s24, 0x2000
	s_nop 0
	global_load_lds_dwordx4 v[52:53], off
	s_waitcnt vmcnt(6)
	s_barrier
	v_mfma_f32_16x16x32_bf16 v[44:47], v[168:171], v[136:139], v[44:47]
	v_mfma_f32_16x16x32_bf16 v[36:39], v[184:187], v[136:139], v[36:39]
	v_mfma_f32_16x16x32_bf16 v[28:31], v[168:171], v[156:159], v[28:31]
	v_mfma_f32_16x16x32_bf16 v[20:23], v[184:187], v[156:159], v[20:23]
	v_mfma_f32_16x16x32_bf16 v[8:11], v[168:171], v[172:175], v[8:11]
	v_mfma_f32_16x16x32_bf16 v[4:7], v[184:187], v[172:175], v[4:7]
	v_mfma_f32_16x16x32_bf16 v[52:55], v[168:171], v[104:107], v[108:111]
	v_mfma_f32_16x16x32_bf16 v[56:59], v[184:187], v[104:107], v[68:71]
	v_mfma_f32_16x16x32_bf16 v[44:47], v[176:179], v[148:151], v[44:47]
	v_mfma_f32_16x16x32_bf16 v[36:39], v[192:195], v[148:151], v[36:39]
	v_mfma_f32_16x16x32_bf16 v[28:31], v[176:179], v[164:167], v[28:31]
	v_mfma_f32_16x16x32_bf16 v[20:23], v[192:195], v[164:167], v[20:23]
	v_mfma_f32_16x16x32_bf16 v[8:11], v[176:179], v[180:183], v[8:11]
	v_mfma_f32_16x16x32_bf16 v[4:7], v[192:195], v[180:183], v[4:7]
	v_mfma_f32_16x16x32_bf16 v[52:55], v[176:179], v[132:135], v[52:55]
	v_mfma_f32_16x16x32_bf16 v[56:59], v[192:195], v[132:135], v[56:59]
	s_add_i32 s24, 0, 0x18000
	v_add_u32_e32 v104, s24, v235
	s_barrier
	ds_read_b128 v[60:63], v104
	ds_read_b128 v[64:67], v104 offset:1024
	ds_read_b128 v[68:71], v104 offset:2048
	ds_read_b128 v[104:107], v104 offset:3072
	s_add_u32 s22, s56, 0x40000
	s_addc_u32 s23, s57, 0
	s_mov_b32 m0, s64
	v_lshl_add_u64 v[156:157], s[22:23], 0, v[204:205]
	ds_read_b128 v[108:111], v239 offset:32768
	ds_read_b128 v[132:135], v239 offset:33792
	ds_read_b128 v[136:139], v239 offset:34816
	ds_read_b128 v[148:151], v239 offset:35840
	ds_read_b128 v[210:213], v239 offset:36864
	ds_read_b128 v[214:217], v239 offset:37888
	ds_read_b128 v[240:243], v239 offset:38912
	ds_read_b128 v[244:247], v239 offset:39936
	global_load_lds_dwordx4 v[156:157], off
	v_lshl_add_u64 v[156:157], s[22:23], 0, v[202:203]
	s_mov_b32 m0, s65
	s_nop 0
	global_load_lds_dwordx4 v[156:157], off
	s_waitcnt lgkmcnt(8)
	s_barrier
	s_waitcnt lgkmcnt(0)
	s_waitcnt lgkmcnt(0)
	v_mfma_f32_16x16x32_bf16 v[116:119], v[60:63], v[108:111], v[116:119]
	v_mfma_f32_16x16x32_bf16 v[192:195], v[64:67], v[132:135], v[116:119]
	v_mfma_f32_16x16x32_bf16 v[116:119], v[68:71], v[108:111], v[120:123]
	v_mfma_f32_16x16x32_bf16 v[184:187], v[104:107], v[132:135], v[116:119]
	v_mfma_f32_16x16x32_bf16 v[116:119], v[60:63], v[136:139], v[124:127]
	v_mfma_f32_16x16x32_bf16 v[176:179], v[64:67], v[148:151], v[116:119]
	v_mfma_f32_16x16x32_bf16 v[116:119], v[68:71], v[136:139], v[128:131]
	v_mfma_f32_16x16x32_bf16 v[168:171], v[104:107], v[148:151], v[116:119]
	v_mfma_f32_16x16x32_bf16 v[116:119], v[60:63], v[210:213], v[160:163]
	v_mfma_f32_16x16x32_bf16 v[160:163], v[64:67], v[214:217], v[116:119]
	v_mfma_f32_16x16x32_bf16 v[116:119], v[68:71], v[210:213], v[152:155]
	v_mfma_f32_16x16x32_bf16 v[152:155], v[104:107], v[214:217], v[116:119]
	v_mfma_f32_16x16x32_bf16 v[116:119], v[60:63], v[240:243], v[144:147]
	v_mfma_f32_16x16x32_bf16 v[144:147], v[64:67], v[244:247], v[116:119]
	v_mfma_f32_16x16x32_bf16 v[116:119], v[68:71], v[240:243], v[140:143]
	v_mfma_f32_16x16x32_bf16 v[140:143], v[104:107], v[244:247], v[116:119]
	s_barrier
	s_add_i32 s25, 0, 0x1c000
	s_add_i32 s22, s24, s60
	v_add_u32_e32 v128, s25, v235
	v_lshl_add_u64 v[156:157], v[198:199], 0, s[76:77]
	s_mov_b32 m0, s22
	ds_read_b128 v[116:119], v128
	ds_read_b128 v[120:123], v128 offset:1024
	ds_read_b128 v[124:127], v128 offset:2048
	ds_read_b128 v[128:131], v128 offset:3072
	global_load_lds_dwordx4 v[156:157], off
	v_lshl_add_u64 v[156:157], v[222:223], 0, s[76:77]
	s_add_i32 m0, s22, 0x2000
	s_nop 0
	global_load_lds_dwordx4 v[156:157], off
	s_barrier
	s_waitcnt lgkmcnt(0)
	s_waitcnt lgkmcnt(0)
	v_mfma_f32_16x16x32_bf16 v[76:79], v[124:127], v[108:111], v[76:79]
	v_mfma_f32_16x16x32_bf16 v[180:183], v[128:131], v[132:135], v[76:79]
	v_mfma_f32_16x16x32_bf16 v[76:79], v[116:119], v[136:139], v[80:83]
	v_mfma_f32_16x16x32_bf16 v[172:175], v[120:123], v[148:151], v[76:79]
	v_mfma_f32_16x16x32_bf16 v[76:79], v[124:127], v[136:139], v[84:87]
	v_mfma_f32_16x16x32_bf16 v[156:159], v[116:119], v[108:111], v[188:191]
	v_mfma_f32_16x16x32_bf16 v[164:167], v[128:131], v[148:151], v[76:79]
	v_mfma_f32_16x16x32_bf16 v[76:79], v[116:119], v[210:213], v[88:91]
	v_mfma_f32_16x16x32_bf16 v[188:191], v[120:123], v[132:135], v[156:159]
	v_mfma_f32_16x16x32_bf16 v[156:159], v[120:123], v[214:217], v[76:79]
	v_mfma_f32_16x16x32_bf16 v[76:79], v[124:127], v[210:213], v[92:95]
	v_mfma_f32_16x16x32_bf16 v[148:151], v[128:131], v[214:217], v[76:79]
	v_mfma_f32_16x16x32_bf16 v[76:79], v[116:119], v[240:243], v[96:99]
	v_mfma_f32_16x16x32_bf16 v[136:139], v[120:123], v[244:247], v[76:79]
	v_mfma_f32_16x16x32_bf16 v[76:79], v[124:127], v[240:243], v[100:103]
	v_mfma_f32_16x16x32_bf16 v[132:135], v[128:131], v[244:247], v[76:79]
	s_mov_b32 m0, s72
	v_lshl_add_u64 v[108:109], v[248:249], 0, s[76:77]
	s_barrier
	s_nop 2
	ds_read_b128 v[76:79], v239 offset:49152
	ds_read_b128 v[80:83], v239 offset:50176
	ds_read_b128 v[84:87], v239 offset:51200
	ds_read_b128 v[88:91], v239 offset:52224
	ds_read_b128 v[92:95], v239 offset:53248
	ds_read_b128 v[96:99], v239 offset:54272
	ds_read_b128 v[100:103], v239 offset:55296
	ds_read_b128 v[210:213], v239 offset:56320
	global_load_lds_dwordx4 v[108:109], off
	v_lshl_add_u64 v[108:109], v[250:251], 0, s[76:77]
	s_mov_b32 m0, s74
	s_nop 0
	global_load_lds_dwordx4 v[108:109], off
	s_barrier
	s_waitcnt lgkmcnt(0)
	s_waitcnt lgkmcnt(0)
	v_mfma_f32_16x16x32_bf16 v[108:111], v[60:63], v[76:79], v[112:115]
	v_mfma_f32_16x16x32_bf16 v[72:75], v[68:71], v[76:79], v[72:75]
	v_mfma_f32_16x16x32_bf16 v[48:51], v[60:63], v[84:87], v[48:51]
	v_mfma_f32_16x16x32_bf16 v[40:43], v[68:71], v[84:87], v[40:43]
	v_mfma_f32_16x16x32_bf16 v[32:35], v[60:63], v[92:95], v[32:35]
	v_mfma_f32_16x16x32_bf16 v[24:27], v[68:71], v[92:95], v[24:27]
	v_mfma_f32_16x16x32_bf16 v[16:19], v[60:63], v[100:103], v[16:19]
	v_mfma_f32_16x16x32_bf16 v[12:15], v[68:71], v[100:103], v[12:15]
	v_mfma_f32_16x16x32_bf16 v[112:115], v[64:67], v[80:83], v[108:111]
	v_mfma_f32_16x16x32_bf16 v[72:75], v[104:107], v[80:83], v[72:75]
	v_mfma_f32_16x16x32_bf16 v[48:51], v[64:67], v[88:91], v[48:51]
	v_mfma_f32_16x16x32_bf16 v[40:43], v[104:107], v[88:91], v[40:43]
	v_mfma_f32_16x16x32_bf16 v[32:35], v[64:67], v[96:99], v[32:35]
	v_mfma_f32_16x16x32_bf16 v[24:27], v[104:107], v[96:99], v[24:27]
	v_mfma_f32_16x16x32_bf16 v[16:19], v[64:67], v[210:213], v[16:19]
	v_mfma_f32_16x16x32_bf16 v[12:15], v[104:107], v[210:213], v[12:15]
	s_barrier
	s_add_u32 s22, s54, 0x40080
	s_addc_u32 s23, s55, 0
	s_add_i32 s24, s25, s60
	v_lshl_add_u64 v[60:61], s[22:23], 0, v[2:3]
	s_mov_b32 m0, s24
	s_nop 0
	global_load_lds_dwordx4 v[60:61], off
	v_lshl_add_u64 v[60:61], s[22:23], 0, v[0:1]
	s_add_i32 m0, s24, 0x2000
	s_nop 0
	global_load_lds_dwordx4 v[60:61], off
	s_waitcnt vmcnt(6)
	s_barrier
	v_mfma_f32_16x16x32_bf16 v[52:55], v[116:119], v[76:79], v[52:55]
	v_mfma_f32_16x16x32_bf16 v[108:111], v[120:123], v[80:83], v[52:55]
	v_mfma_f32_16x16x32_bf16 v[52:55], v[124:127], v[76:79], v[56:59]
	v_mfma_f32_16x16x32_bf16 v[44:47], v[116:119], v[84:87], v[44:47]
	v_mfma_f32_16x16x32_bf16 v[36:39], v[124:127], v[84:87], v[36:39]
	v_mfma_f32_16x16x32_bf16 v[28:31], v[116:119], v[92:95], v[28:31]
	v_mfma_f32_16x16x32_bf16 v[20:23], v[124:127], v[92:95], v[20:23]
	v_mfma_f32_16x16x32_bf16 v[8:11], v[116:119], v[100:103], v[8:11]
	v_mfma_f32_16x16x32_bf16 v[4:7], v[124:127], v[100:103], v[4:7]
	v_mfma_f32_16x16x32_bf16 v[68:71], v[128:131], v[80:83], v[52:55]
	v_mfma_f32_16x16x32_bf16 v[44:47], v[120:123], v[88:91], v[44:47]
	v_mfma_f32_16x16x32_bf16 v[36:39], v[128:131], v[88:91], v[36:39]
	v_mfma_f32_16x16x32_bf16 v[28:31], v[120:123], v[96:99], v[28:31]
	v_mfma_f32_16x16x32_bf16 v[20:23], v[128:131], v[96:99], v[20:23]
	v_mfma_f32_16x16x32_bf16 v[8:11], v[120:123], v[210:213], v[8:11]
	v_mfma_f32_16x16x32_bf16 v[4:7], v[128:131], v[210:213], v[4:7]
	s_add_i32 s21, s21, 2
	s_add_u32 s52, s52, 0x100
	s_addc_u32 s53, s53, 0
	s_add_u32 s1, s1, 0x100
	s_addc_u32 s20, s20, 0
	s_cmp_gt_u32 s21, 13
	s_barrier
	s_cbranch_scc0 .LBB0_80
	v_lshl_or_b32 v210, s30, 7, v238
	s_lshl_b32 s1, s50, 8
	s_add_i32 s1, s1, s67
	v_lshlrev_b32_e32 v211, 2, v210
	v_lshlrev_b32_e32 v219, 1, v210
	v_readlane_b32 s2, v252, 4
	v_readlane_b32 s3, v252, 5
	v_readlane_b32 s20, v252, 20
	v_readlane_b32 s21, v252, 21
	v_readlane_b32 s22, v252, 2
	v_readlane_b32 s23, v252, 3
	v_readlane_b32 s24, v252, 22
	v_readlane_b32 s25, v252, 23
	v_readlane_b32 s26, v252, 24
	v_readlane_b32 s27, v252, 25
	v_readlane_b32 s50, v252, 26
	v_readlane_b32 s51, v252, 27
	v_readlane_b32 s56, v252, 28
	v_readlane_b32 s57, v252, 29
	v_readlane_b32 s98, v252, 30
	v_readlane_b32 s99, v252, 31
	v_lshl_add_u32 v240, v201, 2, s1
	v_mul_u32_u24_e32 v240, 0x1600, v240
	v_add_u32_e32 v240, v240, v219
	global_load_dwordx4 v[120:123], v211, s[2:3]
	global_load_dwordx4 v[80:83], v211, s[2:3] offset:16
	global_load_dwordx4 v[116:119], v211, s[20:21]
	global_load_dwordx4 v[76:79], v211, s[20:21] offset:16
	global_load_dwordx4 v[96:99], v211, s[22:23]
	global_load_dwordx4 v[56:59], v211, s[22:23] offset:16
	global_load_dwordx4 v[92:95], v211, s[24:25]
	global_load_dwordx4 v[52:55], v211, s[24:25] offset:16
	global_load_dwordx4 v[104:107], v211, s[26:27]
	global_load_dwordx4 v[64:67], v211, s[26:27] offset:16
	global_load_dwordx4 v[100:103], v211, s[50:51]
	global_load_dwordx4 v[60:63], v211, s[50:51] offset:16
	global_load_dwordx4 v[124:127], v211, s[56:57]
	global_load_dwordx4 v[84:87], v211, s[56:57] offset:16
	global_load_dwordx4 v[128:131], v211, s[98:99]
	global_load_dwordx4 v[88:91], v211, s[98:99] offset:16
	v_readlane_b32 s56, v254, 63
	v_readlane_b32 s57, v255, 0
	v_cmp_eq_u32_e64 s[2:3], 0, v201
	v_cmp_eq_u32_e64 s[26:27], 15, v201
	s_lshr_b32 s24, s1, 4
	s_mov_b64 exec, s[2:3]
	v_cvt_pk_bf16_f32 v212, v192, v193
	v_cvt_pk_bf16_f32 v213, v194, v195
	v_cvt_pk_bf16_f32 v214, v184, v185
	v_cvt_pk_bf16_f32 v215, v186, v187
	s_add_i32 s20, s24, 2
	s_mulk_i32 s20, 0x2c00
	s_add_u32 s22, s56, s20
	s_addc_u32 s23, s57, 0
	global_store_dwordx4 v219, v[212:215], s[22:23]
	v_cvt_pk_bf16_f32 v242, v188, v189
	v_cvt_pk_bf16_f32 v243, v190, v191
	v_cvt_pk_bf16_f32 v244, v180, v181
	v_cvt_pk_bf16_f32 v245, v182, v183
	s_add_u32 s22, s22, 0x1600
	s_addc_u32 s23, s23, 0
	global_store_dwordx4 v219, v[242:245], s[22:23]
	v_cvt_pk_bf16_f32 v246, v176, v177
	v_cvt_pk_bf16_f32 v247, v178, v179
	v_cvt_pk_bf16_f32 v248, v168, v169
	v_cvt_pk_bf16_f32 v249, v170, v171
	s_add_i32 s20, s24, 3
	s_mulk_i32 s20, 0x2c00
	s_add_u32 s22, s56, s20
	s_addc_u32 s23, s57, 0
	global_store_dwordx4 v219, v[246:249], s[22:23]
	v_cvt_pk_bf16_f32 v212, v172, v173
	v_cvt_pk_bf16_f32 v213, v174, v175
	v_cvt_pk_bf16_f32 v214, v164, v165
	v_cvt_pk_bf16_f32 v215, v166, v167
	s_add_u32 s22, s22, 0x1600
	s_addc_u32 s23, s23, 0
	global_store_dwordx4 v219, v[212:215], s[22:23]
	s_mov_b64 exec, s[26:27]
	v_cvt_pk_bf16_f32 v242, v160, v161
	v_cvt_pk_bf16_f32 v243, v162, v163
	v_cvt_pk_bf16_f32 v244, v152, v153
	v_cvt_pk_bf16_f32 v245, v154, v155
	s_add_i32 s20, s24, 0
	s_mulk_i32 s20, 0x2c00
	s_add_u32 s22, s56, s20
	s_addc_u32 s23, s57, 0
	global_store_dwordx4 v219, v[242:245], s[22:23]
	v_cvt_pk_bf16_f32 v246, v156, v157
	v_cvt_pk_bf16_f32 v247, v158, v159
	v_cvt_pk_bf16_f32 v248, v148, v149
	v_cvt_pk_bf16_f32 v249, v150, v151
	s_add_u32 s22, s22, 0x1600
	s_addc_u32 s23, s23, 0
	global_store_dwordx4 v219, v[246:249], s[22:23]
	v_cvt_pk_bf16_f32 v212, v144, v145
	v_cvt_pk_bf16_f32 v213, v146, v147
	v_cvt_pk_bf16_f32 v214, v140, v141
	v_cvt_pk_bf16_f32 v215, v142, v143
	s_add_i32 s20, s24, 1
	s_mulk_i32 s20, 0x2c00
	s_add_u32 s22, s56, s20
	s_addc_u32 s23, s57, 0
	global_store_dwordx4 v219, v[212:215], s[22:23]
	v_cvt_pk_bf16_f32 v242, v136, v137
	v_cvt_pk_bf16_f32 v243, v138, v139
	v_cvt_pk_bf16_f32 v244, v132, v133
	v_cvt_pk_bf16_f32 v245, v134, v135
	s_add_u32 s22, s22, 0x1600
	s_addc_u32 s23, s23, 0
	global_store_dwordx4 v219, v[242:245], s[22:23]
	s_mov_b64 exec, s[2:3]
	v_cvt_pk_bf16_f32 v246, v112, v113
	v_cvt_pk_bf16_f32 v247, v114, v115
	v_cvt_pk_bf16_f32 v248, v72, v73
	v_cvt_pk_bf16_f32 v249, v74, v75
	s_add_i32 s20, s24, 10
	s_mulk_i32 s20, 0x2c00
	s_add_u32 s22, s56, s20
	s_addc_u32 s23, s57, 0
	global_store_dwordx4 v219, v[246:249], s[22:23]
	v_cvt_pk_bf16_f32 v212, v108, v109
	v_cvt_pk_bf16_f32 v213, v110, v111
	v_cvt_pk_bf16_f32 v214, v68, v69
	v_cvt_pk_bf16_f32 v215, v70, v71
	s_add_u32 s22, s22, 0x1600
	s_addc_u32 s23, s23, 0
	global_store_dwordx4 v219, v[212:215], s[22:23]
	v_cvt_pk_bf16_f32 v242, v48, v49
	v_cvt_pk_bf16_f32 v243, v50, v51
	v_cvt_pk_bf16_f32 v244, v40, v41
	v_cvt_pk_bf16_f32 v245, v42, v43
	s_add_i32 s20, s24, 11
	s_mulk_i32 s20, 0x2c00
	s_add_u32 s22, s56, s20
	s_addc_u32 s23, s57, 0
	global_store_dwordx4 v219, v[242:245], s[22:23]
	v_cvt_pk_bf16_f32 v246, v44, v45
	v_cvt_pk_bf16_f32 v247, v46, v47
	v_cvt_pk_bf16_f32 v248, v36, v37
	v_cvt_pk_bf16_f32 v249, v38, v39
	s_add_u32 s22, s22, 0x1600
	s_addc_u32 s23, s23, 0
	global_store_dwordx4 v219, v[246:249], s[22:23]
	s_mov_b64 exec, s[26:27]
	v_cvt_pk_bf16_f32 v212, v32, v33
	v_cvt_pk_bf16_f32 v213, v34, v35
	v_cvt_pk_bf16_f32 v214, v24, v25
	v_cvt_pk_bf16_f32 v215, v26, v27
	s_add_i32 s20, s24, 8
	s_mulk_i32 s20, 0x2c00
	s_add_u32 s22, s56, s20
	s_addc_u32 s23, s57, 0
	global_store_dwordx4 v219, v[212:215], s[22:23]
	v_cvt_pk_bf16_f32 v242, v28, v29
	v_cvt_pk_bf16_f32 v243, v30, v31
	v_cvt_pk_bf16_f32 v244, v20, v21
	v_cvt_pk_bf16_f32 v245, v22, v23
	s_add_u32 s22, s22, 0x1600
	s_addc_u32 s23, s23, 0
	global_store_dwordx4 v219, v[242:245], s[22:23]
	v_cvt_pk_bf16_f32 v246, v16, v17
	v_cvt_pk_bf16_f32 v247, v18, v19
	v_cvt_pk_bf16_f32 v248, v12, v13
	v_cvt_pk_bf16_f32 v249, v14, v15
	s_add_i32 s20, s24, 9
	s_mulk_i32 s20, 0x2c00
	s_add_u32 s22, s56, s20
	s_addc_u32 s23, s57, 0
	global_store_dwordx4 v219, v[246:249], s[22:23]
	v_cvt_pk_bf16_f32 v212, v8, v9
	v_cvt_pk_bf16_f32 v213, v10, v11
	v_cvt_pk_bf16_f32 v214, v4, v5
	v_cvt_pk_bf16_f32 v215, v6, v7
	s_add_u32 s22, s22, 0x1600
	s_addc_u32 s23, s23, 0
	global_store_dwordx4 v219, v[212:215], s[22:23]
	s_mov_b64 exec, -1
	s_mov_b32 s50, 0xbfb8aa3b
	s_mov_b32 s51, 0xbfb8aa3b
	s_waitcnt vmcnt(16)
	v_mov_b32_dpp v198, v144 row_shr:1 row_mask:0xf bank_mask:0xf bound_ctrl:1
	v_mov_b32_dpp v199, v145 row_shr:1 row_mask:0xf bank_mask:0xf bound_ctrl:1
	v_mov_b32_dpp v214, v136 row_shr:1 row_mask:0xf bank_mask:0xf bound_ctrl:1
	v_mov_b32_dpp v215, v137 row_shr:1 row_mask:0xf bank_mask:0xf bound_ctrl:1
	v_mov_b32_dpp v212, v160 row_shr:1 row_mask:0xf bank_mask:0xf bound_ctrl:1
	v_mov_b32_dpp v213, v161 row_shr:1 row_mask:0xf bank_mask:0xf bound_ctrl:1
	v_mov_b32_dpp v216, v156 row_shr:1 row_mask:0xf bank_mask:0xf bound_ctrl:1
	v_mov_b32_dpp v217, v157 row_shr:1 row_mask:0xf bank_mask:0xf bound_ctrl:1
	v_pk_fma_f32 v[144:145], v[144:145], v[124:125], v[120:121]
	v_pk_fma_f32 v[136:137], v[136:137], v[128:129], v[116:117]
	v_pk_fma_f32 v[144:145], v[160:161], v[104:105], v[144:145]
	v_pk_fma_f32 v[136:137], v[156:157], v[100:101], v[136:137]
	v_pk_fma_f32 v[144:145], v[176:177], v[96:97], v[144:145]
	v_pk_fma_f32 v[136:137], v[172:173], v[92:93], v[136:137]
	v_pk_fma_f32 v[160:161], v[160:161], v[124:125], v[120:121]
	v_pk_fma_f32 v[156:157], v[156:157], v[128:129], v[116:117]
	v_pk_fma_f32 v[160:161], v[176:177], v[104:105], v[160:161]
	v_pk_fma_f32 v[156:157], v[172:173], v[100:101], v[156:157]
	v_pk_fma_f32 v[160:161], v[192:193], v[96:97], v[160:161]
	v_pk_fma_f32 v[156:157], v[188:189], v[92:93], v[156:157]
	v_pk_fma_f32 v[176:177], v[176:177], v[124:125], v[120:121]
	v_pk_fma_f32 v[172:173], v[172:173], v[128:129], v[116:117]
	v_pk_fma_f32 v[176:177], v[192:193], v[104:105], v[176:177]
	v_pk_fma_f32 v[172:173], v[188:189], v[100:101], v[172:173]
	v_pk_fma_f32 v[176:177], v[198:199], v[96:97], v[176:177]
	v_pk_fma_f32 v[172:173], v[214:215], v[92:93], v[172:173]
	v_pk_fma_f32 v[192:193], v[192:193], v[124:125], v[120:121]
	v_pk_fma_f32 v[188:189], v[188:189], v[128:129], v[116:117]
	v_pk_fma_f32 v[192:193], v[198:199], v[104:105], v[192:193]
	v_pk_fma_f32 v[188:189], v[214:215], v[100:101], v[188:189]
	v_pk_fma_f32 v[192:193], v[212:213], v[96:97], v[192:193]
	v_pk_fma_f32 v[188:189], v[216:217], v[92:93], v[188:189]
	v_pk_mul_f32 v[222:223], v[192:193], s[50:51]
	v_pk_mul_f32 v[242:243], v[176:177], s[50:51]
	v_pk_mul_f32 v[244:245], v[160:161], s[50:51]
	v_pk_mul_f32 v[246:247], v[144:145], s[50:51]
	v_exp_f32_e32 v222, v222
	v_exp_f32_e32 v223, v223
	v_exp_f32_e32 v242, v242
	v_exp_f32_e32 v243, v243
	v_exp_f32_e32 v244, v244
	v_exp_f32_e32 v245, v245
	v_exp_f32_e32 v246, v246
	v_exp_f32_e32 v247, v247
	v_pk_add_f32 v[222:223], v[222:223], 1.0 op_sel_hi:[1,0]
	v_pk_add_f32 v[242:243], v[242:243], 1.0 op_sel_hi:[1,0]
	v_pk_add_f32 v[244:245], v[244:245], 1.0 op_sel_hi:[1,0]
	v_pk_add_f32 v[246:247], v[246:247], 1.0 op_sel_hi:[1,0]
	v_rcp_f32_e32 v222, v222
	v_rcp_f32_e32 v223, v223
	v_rcp_f32_e32 v242, v242
	v_rcp_f32_e32 v243, v243
	v_rcp_f32_e32 v244, v244
	v_rcp_f32_e32 v245, v245
	v_rcp_f32_e32 v246, v246
	v_rcp_f32_e32 v247, v247
	v_pk_mul_f32 v[192:193], v[192:193], v[222:223]
	v_pk_mul_f32 v[176:177], v[176:177], v[242:243]
	v_pk_mul_f32 v[160:161], v[160:161], v[244:245]
	v_pk_mul_f32 v[144:145], v[144:145], v[246:247]
	v_pk_mul_f32 v[192:193], v[192:193], v[188:189]
	v_pk_mul_f32 v[176:177], v[176:177], v[172:173]
	v_pk_mul_f32 v[160:161], v[160:161], v[156:157]
	v_pk_mul_f32 v[144:145], v[144:145], v[136:137]
	v_cvt_pk_bf16_f32 v192, v192, v193
	v_cvt_pk_bf16_f32 v176, v176, v177
	v_cvt_pk_bf16_f32 v160, v160, v161
	v_cvt_pk_bf16_f32 v144, v144, v145
	v_mov_b32_dpp v198, v146 row_shr:1 row_mask:0xf bank_mask:0xf bound_ctrl:1
	v_mov_b32_dpp v199, v147 row_shr:1 row_mask:0xf bank_mask:0xf bound_ctrl:1
	v_mov_b32_dpp v214, v138 row_shr:1 row_mask:0xf bank_mask:0xf bound_ctrl:1
	v_mov_b32_dpp v215, v139 row_shr:1 row_mask:0xf bank_mask:0xf bound_ctrl:1
	v_mov_b32_dpp v212, v162 row_shr:1 row_mask:0xf bank_mask:0xf bound_ctrl:1
	v_mov_b32_dpp v213, v163 row_shr:1 row_mask:0xf bank_mask:0xf bound_ctrl:1
	v_mov_b32_dpp v216, v158 row_shr:1 row_mask:0xf bank_mask:0xf bound_ctrl:1
	v_mov_b32_dpp v217, v159 row_shr:1 row_mask:0xf bank_mask:0xf bound_ctrl:1
	v_pk_fma_f32 v[146:147], v[146:147], v[126:127], v[122:123]
	v_pk_fma_f32 v[138:139], v[138:139], v[130:131], v[118:119]
	v_pk_fma_f32 v[146:147], v[162:163], v[106:107], v[146:147]
	v_pk_fma_f32 v[138:139], v[158:159], v[102:103], v[138:139]
	v_pk_fma_f32 v[146:147], v[178:179], v[98:99], v[146:147]
	v_pk_fma_f32 v[138:139], v[174:175], v[94:95], v[138:139]
	v_pk_fma_f32 v[162:163], v[162:163], v[126:127], v[122:123]
	v_pk_fma_f32 v[158:159], v[158:159], v[130:131], v[118:119]
	v_pk_fma_f32 v[162:163], v[178:179], v[106:107], v[162:163]
	v_pk_fma_f32 v[158:159], v[174:175], v[102:103], v[158:159]
	v_pk_fma_f32 v[162:163], v[194:195], v[98:99], v[162:163]
	v_pk_fma_f32 v[158:159], v[190:191], v[94:95], v[158:159]
	v_pk_fma_f32 v[178:179], v[178:179], v[126:127], v[122:123]
	v_pk_fma_f32 v[174:175], v[174:175], v[130:131], v[118:119]
	v_pk_fma_f32 v[178:179], v[194:195], v[106:107], v[178:179]
	v_pk_fma_f32 v[174:175], v[190:191], v[102:103], v[174:175]
	v_pk_fma_f32 v[178:179], v[198:199], v[98:99], v[178:179]
	v_pk_fma_f32 v[174:175], v[214:215], v[94:95], v[174:175]
	v_pk_fma_f32 v[194:195], v[194:195], v[126:127], v[122:123]
	v_pk_fma_f32 v[190:191], v[190:191], v[130:131], v[118:119]
	v_pk_fma_f32 v[194:195], v[198:199], v[106:107], v[194:195]
	v_pk_fma_f32 v[190:191], v[214:215], v[102:103], v[190:191]
	v_pk_fma_f32 v[194:195], v[212:213], v[98:99], v[194:195]
	v_pk_fma_f32 v[190:191], v[216:217], v[94:95], v[190:191]
	v_pk_mul_f32 v[222:223], v[194:195], s[50:51]
	v_pk_mul_f32 v[242:243], v[178:179], s[50:51]
	v_pk_mul_f32 v[244:245], v[162:163], s[50:51]
	v_pk_mul_f32 v[246:247], v[146:147], s[50:51]
	v_exp_f32_e32 v222, v222
	v_exp_f32_e32 v223, v223
	v_exp_f32_e32 v242, v242
	v_exp_f32_e32 v243, v243
	v_exp_f32_e32 v244, v244
	v_exp_f32_e32 v245, v245
	v_exp_f32_e32 v246, v246
	v_exp_f32_e32 v247, v247
	v_pk_add_f32 v[222:223], v[222:223], 1.0 op_sel_hi:[1,0]
	v_pk_add_f32 v[242:243], v[242:243], 1.0 op_sel_hi:[1,0]
	v_pk_add_f32 v[244:245], v[244:245], 1.0 op_sel_hi:[1,0]
	v_pk_add_f32 v[246:247], v[246:247], 1.0 op_sel_hi:[1,0]
	v_rcp_f32_e32 v222, v222
	v_rcp_f32_e32 v223, v223
	v_rcp_f32_e32 v242, v242
	v_rcp_f32_e32 v243, v243
	v_rcp_f32_e32 v244, v244
	v_rcp_f32_e32 v245, v245
	v_rcp_f32_e32 v246, v246
	v_rcp_f32_e32 v247, v247
	v_pk_mul_f32 v[194:195], v[194:195], v[222:223]
	v_pk_mul_f32 v[178:179], v[178:179], v[242:243]
	v_pk_mul_f32 v[162:163], v[162:163], v[244:245]
	v_pk_mul_f32 v[146:147], v[146:147], v[246:247]
	v_pk_mul_f32 v[194:195], v[194:195], v[190:191]
	v_pk_mul_f32 v[178:179], v[178:179], v[174:175]
	v_pk_mul_f32 v[162:163], v[162:163], v[158:159]
	v_pk_mul_f32 v[146:147], v[146:147], v[138:139]
	v_cvt_pk_bf16_f32 v193, v194, v195
	v_cvt_pk_bf16_f32 v177, v178, v179
	v_cvt_pk_bf16_f32 v161, v162, v163
	v_cvt_pk_bf16_f32 v145, v146, v147
	v_mov_b32_dpp v198, v140 row_shr:1 row_mask:0xf bank_mask:0xf bound_ctrl:1
	v_mov_b32_dpp v199, v141 row_shr:1 row_mask:0xf bank_mask:0xf bound_ctrl:1
	v_mov_b32_dpp v214, v132 row_shr:1 row_mask:0xf bank_mask:0xf bound_ctrl:1
	v_mov_b32_dpp v215, v133 row_shr:1 row_mask:0xf bank_mask:0xf bound_ctrl:1
	v_mov_b32_dpp v212, v152 row_shr:1 row_mask:0xf bank_mask:0xf bound_ctrl:1
	v_mov_b32_dpp v213, v153 row_shr:1 row_mask:0xf bank_mask:0xf bound_ctrl:1
	v_mov_b32_dpp v216, v148 row_shr:1 row_mask:0xf bank_mask:0xf bound_ctrl:1
	v_mov_b32_dpp v217, v149 row_shr:1 row_mask:0xf bank_mask:0xf bound_ctrl:1
	v_pk_fma_f32 v[140:141], v[140:141], v[84:85], v[80:81]
	v_pk_fma_f32 v[132:133], v[132:133], v[88:89], v[76:77]
	v_pk_fma_f32 v[140:141], v[152:153], v[64:65], v[140:141]
	v_pk_fma_f32 v[132:133], v[148:149], v[60:61], v[132:133]
	v_pk_fma_f32 v[140:141], v[168:169], v[56:57], v[140:141]
	v_pk_fma_f32 v[132:133], v[164:165], v[52:53], v[132:133]
	v_pk_fma_f32 v[152:153], v[152:153], v[84:85], v[80:81]
	v_pk_fma_f32 v[148:149], v[148:149], v[88:89], v[76:77]
	v_pk_fma_f32 v[152:153], v[168:169], v[64:65], v[152:153]
	v_pk_fma_f32 v[148:149], v[164:165], v[60:61], v[148:149]
	v_pk_fma_f32 v[152:153], v[184:185], v[56:57], v[152:153]
	v_pk_fma_f32 v[148:149], v[180:181], v[52:53], v[148:149]
	v_pk_fma_f32 v[168:169], v[168:169], v[84:85], v[80:81]
	v_pk_fma_f32 v[164:165], v[164:165], v[88:89], v[76:77]
	v_pk_fma_f32 v[168:169], v[184:185], v[64:65], v[168:169]
	v_pk_fma_f32 v[164:165], v[180:181], v[60:61], v[164:165]
	v_pk_fma_f32 v[168:169], v[198:199], v[56:57], v[168:169]
	v_pk_fma_f32 v[164:165], v[214:215], v[52:53], v[164:165]
	v_pk_fma_f32 v[184:185], v[184:185], v[84:85], v[80:81]
	v_pk_fma_f32 v[180:181], v[180:181], v[88:89], v[76:77]
	v_pk_fma_f32 v[184:185], v[198:199], v[64:65], v[184:185]
	v_pk_fma_f32 v[180:181], v[214:215], v[60:61], v[180:181]
	v_pk_fma_f32 v[184:185], v[212:213], v[56:57], v[184:185]
	v_pk_fma_f32 v[180:181], v[216:217], v[52:53], v[180:181]
	v_pk_mul_f32 v[222:223], v[184:185], s[50:51]
	v_pk_mul_f32 v[242:243], v[168:169], s[50:51]
	v_pk_mul_f32 v[244:245], v[152:153], s[50:51]
	v_pk_mul_f32 v[246:247], v[140:141], s[50:51]
	v_exp_f32_e32 v222, v222
	v_exp_f32_e32 v223, v223
	v_exp_f32_e32 v242, v242
	v_exp_f32_e32 v243, v243
	v_exp_f32_e32 v244, v244
	v_exp_f32_e32 v245, v245
	v_exp_f32_e32 v246, v246
	v_exp_f32_e32 v247, v247
	v_pk_add_f32 v[222:223], v[222:223], 1.0 op_sel_hi:[1,0]
	v_pk_add_f32 v[242:243], v[242:243], 1.0 op_sel_hi:[1,0]
	v_pk_add_f32 v[244:245], v[244:245], 1.0 op_sel_hi:[1,0]
	v_pk_add_f32 v[246:247], v[246:247], 1.0 op_sel_hi:[1,0]
	v_rcp_f32_e32 v222, v222
	v_rcp_f32_e32 v223, v223
	v_rcp_f32_e32 v242, v242
	v_rcp_f32_e32 v243, v243
	v_rcp_f32_e32 v244, v244
	v_rcp_f32_e32 v245, v245
	v_rcp_f32_e32 v246, v246
	v_rcp_f32_e32 v247, v247
	v_pk_mul_f32 v[184:185], v[184:185], v[222:223]
	v_pk_mul_f32 v[168:169], v[168:169], v[242:243]
	v_pk_mul_f32 v[152:153], v[152:153], v[244:245]
	v_pk_mul_f32 v[140:141], v[140:141], v[246:247]
	v_pk_mul_f32 v[184:185], v[184:185], v[180:181]
	v_pk_mul_f32 v[168:169], v[168:169], v[164:165]
	v_pk_mul_f32 v[152:153], v[152:153], v[148:149]
	v_pk_mul_f32 v[140:141], v[140:141], v[132:133]
	v_cvt_pk_bf16_f32 v194, v184, v185
	v_cvt_pk_bf16_f32 v178, v168, v169
	v_cvt_pk_bf16_f32 v162, v152, v153
	v_cvt_pk_bf16_f32 v146, v140, v141
	v_mov_b32_dpp v198, v142 row_shr:1 row_mask:0xf bank_mask:0xf bound_ctrl:1
	v_mov_b32_dpp v199, v143 row_shr:1 row_mask:0xf bank_mask:0xf bound_ctrl:1
	v_mov_b32_dpp v214, v134 row_shr:1 row_mask:0xf bank_mask:0xf bound_ctrl:1
	v_mov_b32_dpp v215, v135 row_shr:1 row_mask:0xf bank_mask:0xf bound_ctrl:1
	v_mov_b32_dpp v212, v154 row_shr:1 row_mask:0xf bank_mask:0xf bound_ctrl:1
	v_mov_b32_dpp v213, v155 row_shr:1 row_mask:0xf bank_mask:0xf bound_ctrl:1
	v_mov_b32_dpp v216, v150 row_shr:1 row_mask:0xf bank_mask:0xf bound_ctrl:1
	v_mov_b32_dpp v217, v151 row_shr:1 row_mask:0xf bank_mask:0xf bound_ctrl:1
	v_pk_fma_f32 v[142:143], v[142:143], v[86:87], v[82:83]
	v_pk_fma_f32 v[134:135], v[134:135], v[90:91], v[78:79]
	v_pk_fma_f32 v[142:143], v[154:155], v[66:67], v[142:143]
	v_pk_fma_f32 v[134:135], v[150:151], v[62:63], v[134:135]
	v_pk_fma_f32 v[142:143], v[170:171], v[58:59], v[142:143]
	v_pk_fma_f32 v[134:135], v[166:167], v[54:55], v[134:135]
	v_pk_fma_f32 v[154:155], v[154:155], v[86:87], v[82:83]
	v_pk_fma_f32 v[150:151], v[150:151], v[90:91], v[78:79]
	v_pk_fma_f32 v[154:155], v[170:171], v[66:67], v[154:155]
	v_pk_fma_f32 v[150:151], v[166:167], v[62:63], v[150:151]
	v_pk_fma_f32 v[154:155], v[186:187], v[58:59], v[154:155]
	v_pk_fma_f32 v[150:151], v[182:183], v[54:55], v[150:151]
	v_pk_fma_f32 v[170:171], v[170:171], v[86:87], v[82:83]
	v_pk_fma_f32 v[166:167], v[166:167], v[90:91], v[78:79]
	v_pk_fma_f32 v[170:171], v[186:187], v[66:67], v[170:171]
	v_pk_fma_f32 v[166:167], v[182:183], v[62:63], v[166:167]
	v_pk_fma_f32 v[170:171], v[198:199], v[58:59], v[170:171]
	v_pk_fma_f32 v[166:167], v[214:215], v[54:55], v[166:167]
	v_pk_fma_f32 v[186:187], v[186:187], v[86:87], v[82:83]
	v_pk_fma_f32 v[182:183], v[182:183], v[90:91], v[78:79]
	v_pk_fma_f32 v[186:187], v[198:199], v[66:67], v[186:187]
	v_pk_fma_f32 v[182:183], v[214:215], v[62:63], v[182:183]
	v_pk_fma_f32 v[186:187], v[212:213], v[58:59], v[186:187]
	v_pk_fma_f32 v[182:183], v[216:217], v[54:55], v[182:183]
	v_pk_mul_f32 v[222:223], v[186:187], s[50:51]
	v_pk_mul_f32 v[242:243], v[170:171], s[50:51]
	v_pk_mul_f32 v[244:245], v[154:155], s[50:51]
	v_pk_mul_f32 v[246:247], v[142:143], s[50:51]
	v_exp_f32_e32 v222, v222
	v_exp_f32_e32 v223, v223
	v_exp_f32_e32 v242, v242
	v_exp_f32_e32 v243, v243
	v_exp_f32_e32 v244, v244
	v_exp_f32_e32 v245, v245
	v_exp_f32_e32 v246, v246
	v_exp_f32_e32 v247, v247
	v_pk_add_f32 v[222:223], v[222:223], 1.0 op_sel_hi:[1,0]
	v_pk_add_f32 v[242:243], v[242:243], 1.0 op_sel_hi:[1,0]
	v_pk_add_f32 v[244:245], v[244:245], 1.0 op_sel_hi:[1,0]
	v_pk_add_f32 v[246:247], v[246:247], 1.0 op_sel_hi:[1,0]
	v_rcp_f32_e32 v222, v222
	v_rcp_f32_e32 v223, v223
	v_rcp_f32_e32 v242, v242
	v_rcp_f32_e32 v243, v243
	v_rcp_f32_e32 v244, v244
	v_rcp_f32_e32 v245, v245
	v_rcp_f32_e32 v246, v246
	v_rcp_f32_e32 v247, v247
	v_pk_mul_f32 v[186:187], v[186:187], v[222:223]
	v_pk_mul_f32 v[170:171], v[170:171], v[242:243]
	v_pk_mul_f32 v[154:155], v[154:155], v[244:245]
	v_pk_mul_f32 v[142:143], v[142:143], v[246:247]
	v_pk_mul_f32 v[186:187], v[186:187], v[182:183]
	v_pk_mul_f32 v[170:171], v[170:171], v[166:167]
	v_pk_mul_f32 v[154:155], v[154:155], v[150:151]
	v_pk_mul_f32 v[142:143], v[142:143], v[134:135]
	v_cvt_pk_bf16_f32 v195, v186, v187
	v_cvt_pk_bf16_f32 v179, v170, v171
	v_cvt_pk_bf16_f32 v163, v154, v155
	v_cvt_pk_bf16_f32 v147, v142, v143
	s_mov_b64 s[20:21], s[82:83]
	global_store_dwordx4 v240, v[192:195], s[20:21]
	s_add_u32 s20, s82, 0x1600
	s_addc_u32 s21, s83, 0
	global_store_dwordx4 v240, v[176:179], s[20:21]
	s_add_u32 s20, s82, 0x2c00
	s_addc_u32 s21, s83, 0
	global_store_dwordx4 v240, v[160:163], s[20:21]
	s_add_u32 s20, s82, 0x4200
	s_addc_u32 s21, s83, 0
	global_store_dwordx4 v240, v[144:147], s[20:21]
	v_mov_b32_dpp v198, v16 row_shr:1 row_mask:0xf bank_mask:0xf bound_ctrl:1
	v_mov_b32_dpp v199, v17 row_shr:1 row_mask:0xf bank_mask:0xf bound_ctrl:1
	v_mov_b32_dpp v214, v8 row_shr:1 row_mask:0xf bank_mask:0xf bound_ctrl:1
	v_mov_b32_dpp v215, v9 row_shr:1 row_mask:0xf bank_mask:0xf bound_ctrl:1
	v_mov_b32_dpp v212, v32 row_shr:1 row_mask:0xf bank_mask:0xf bound_ctrl:1
	v_mov_b32_dpp v213, v33 row_shr:1 row_mask:0xf bank_mask:0xf bound_ctrl:1
	v_mov_b32_dpp v216, v28 row_shr:1 row_mask:0xf bank_mask:0xf bound_ctrl:1
	v_mov_b32_dpp v217, v29 row_shr:1 row_mask:0xf bank_mask:0xf bound_ctrl:1
	v_pk_fma_f32 v[16:17], v[16:17], v[124:125], v[120:121]
	v_pk_fma_f32 v[8:9], v[8:9], v[128:129], v[116:117]
	v_pk_fma_f32 v[16:17], v[32:33], v[104:105], v[16:17]
	v_pk_fma_f32 v[8:9], v[28:29], v[100:101], v[8:9]
	v_pk_fma_f32 v[16:17], v[48:49], v[96:97], v[16:17]
	v_pk_fma_f32 v[8:9], v[44:45], v[92:93], v[8:9]
	v_pk_fma_f32 v[32:33], v[32:33], v[124:125], v[120:121]
	v_pk_fma_f32 v[28:29], v[28:29], v[128:129], v[116:117]
	v_pk_fma_f32 v[32:33], v[48:49], v[104:105], v[32:33]
	v_pk_fma_f32 v[28:29], v[44:45], v[100:101], v[28:29]
	v_pk_fma_f32 v[32:33], v[112:113], v[96:97], v[32:33]
	v_pk_fma_f32 v[28:29], v[108:109], v[92:93], v[28:29]
	v_pk_fma_f32 v[48:49], v[48:49], v[124:125], v[120:121]
	v_pk_fma_f32 v[44:45], v[44:45], v[128:129], v[116:117]
	v_pk_fma_f32 v[48:49], v[112:113], v[104:105], v[48:49]
	v_pk_fma_f32 v[44:45], v[108:109], v[100:101], v[44:45]
	v_pk_fma_f32 v[48:49], v[198:199], v[96:97], v[48:49]
	v_pk_fma_f32 v[44:45], v[214:215], v[92:93], v[44:45]
	v_pk_fma_f32 v[112:113], v[112:113], v[124:125], v[120:121]
	v_pk_fma_f32 v[108:109], v[108:109], v[128:129], v[116:117]
	v_pk_fma_f32 v[112:113], v[198:199], v[104:105], v[112:113]
	v_pk_fma_f32 v[108:109], v[214:215], v[100:101], v[108:109]
	v_pk_fma_f32 v[112:113], v[212:213], v[96:97], v[112:113]
	v_pk_fma_f32 v[108:109], v[216:217], v[92:93], v[108:109]
	v_pk_mul_f32 v[222:223], v[112:113], s[50:51]
	v_pk_mul_f32 v[242:243], v[48:49], s[50:51]
	v_pk_mul_f32 v[244:245], v[32:33], s[50:51]
	v_pk_mul_f32 v[246:247], v[16:17], s[50:51]
	v_exp_f32_e32 v222, v222
	v_exp_f32_e32 v223, v223
	v_exp_f32_e32 v242, v242
	v_exp_f32_e32 v243, v243
	v_exp_f32_e32 v244, v244
	v_exp_f32_e32 v245, v245
	v_exp_f32_e32 v246, v246
	v_exp_f32_e32 v247, v247
	v_pk_add_f32 v[222:223], v[222:223], 1.0 op_sel_hi:[1,0]
	v_pk_add_f32 v[242:243], v[242:243], 1.0 op_sel_hi:[1,0]
	v_pk_add_f32 v[244:245], v[244:245], 1.0 op_sel_hi:[1,0]
	v_pk_add_f32 v[246:247], v[246:247], 1.0 op_sel_hi:[1,0]
	v_rcp_f32_e32 v222, v222
	v_rcp_f32_e32 v223, v223
	v_rcp_f32_e32 v242, v242
	v_rcp_f32_e32 v243, v243
	v_rcp_f32_e32 v244, v244
	v_rcp_f32_e32 v245, v245
	v_rcp_f32_e32 v246, v246
	v_rcp_f32_e32 v247, v247
	v_pk_mul_f32 v[112:113], v[112:113], v[222:223]
	v_pk_mul_f32 v[48:49], v[48:49], v[242:243]
	v_pk_mul_f32 v[32:33], v[32:33], v[244:245]
	v_pk_mul_f32 v[16:17], v[16:17], v[246:247]
	v_pk_mul_f32 v[112:113], v[112:113], v[108:109]
	v_pk_mul_f32 v[48:49], v[48:49], v[44:45]
	v_pk_mul_f32 v[32:33], v[32:33], v[28:29]
	v_pk_mul_f32 v[16:17], v[16:17], v[8:9]
	v_cvt_pk_bf16_f32 v112, v112, v113
	v_cvt_pk_bf16_f32 v48, v48, v49
	v_cvt_pk_bf16_f32 v32, v32, v33
	v_cvt_pk_bf16_f32 v16, v16, v17
	v_mov_b32_dpp v198, v18 row_shr:1 row_mask:0xf bank_mask:0xf bound_ctrl:1
	v_mov_b32_dpp v199, v19 row_shr:1 row_mask:0xf bank_mask:0xf bound_ctrl:1
	v_mov_b32_dpp v214, v10 row_shr:1 row_mask:0xf bank_mask:0xf bound_ctrl:1
	v_mov_b32_dpp v215, v11 row_shr:1 row_mask:0xf bank_mask:0xf bound_ctrl:1
	v_mov_b32_dpp v212, v34 row_shr:1 row_mask:0xf bank_mask:0xf bound_ctrl:1
	v_mov_b32_dpp v213, v35 row_shr:1 row_mask:0xf bank_mask:0xf bound_ctrl:1
	v_mov_b32_dpp v216, v30 row_shr:1 row_mask:0xf bank_mask:0xf bound_ctrl:1
	v_mov_b32_dpp v217, v31 row_shr:1 row_mask:0xf bank_mask:0xf bound_ctrl:1
	v_pk_fma_f32 v[18:19], v[18:19], v[126:127], v[122:123]
	v_pk_fma_f32 v[10:11], v[10:11], v[130:131], v[118:119]
	v_pk_fma_f32 v[18:19], v[34:35], v[106:107], v[18:19]
	v_pk_fma_f32 v[10:11], v[30:31], v[102:103], v[10:11]
	v_pk_fma_f32 v[18:19], v[50:51], v[98:99], v[18:19]
	v_pk_fma_f32 v[10:11], v[46:47], v[94:95], v[10:11]
	v_pk_fma_f32 v[34:35], v[34:35], v[126:127], v[122:123]
	v_pk_fma_f32 v[30:31], v[30:31], v[130:131], v[118:119]
	v_pk_fma_f32 v[34:35], v[50:51], v[106:107], v[34:35]
	v_pk_fma_f32 v[30:31], v[46:47], v[102:103], v[30:31]
	v_pk_fma_f32 v[34:35], v[114:115], v[98:99], v[34:35]
	v_pk_fma_f32 v[30:31], v[110:111], v[94:95], v[30:31]
	v_pk_fma_f32 v[50:51], v[50:51], v[126:127], v[122:123]
	v_pk_fma_f32 v[46:47], v[46:47], v[130:131], v[118:119]
	v_pk_fma_f32 v[50:51], v[114:115], v[106:107], v[50:51]
	v_pk_fma_f32 v[46:47], v[110:111], v[102:103], v[46:47]
	v_pk_fma_f32 v[50:51], v[198:199], v[98:99], v[50:51]
	v_pk_fma_f32 v[46:47], v[214:215], v[94:95], v[46:47]
	v_pk_fma_f32 v[114:115], v[114:115], v[126:127], v[122:123]
	v_pk_fma_f32 v[110:111], v[110:111], v[130:131], v[118:119]
	v_pk_fma_f32 v[114:115], v[198:199], v[106:107], v[114:115]
	v_pk_fma_f32 v[110:111], v[214:215], v[102:103], v[110:111]
	v_pk_fma_f32 v[114:115], v[212:213], v[98:99], v[114:115]
	v_pk_fma_f32 v[110:111], v[216:217], v[94:95], v[110:111]
	v_pk_mul_f32 v[222:223], v[114:115], s[50:51]
	v_pk_mul_f32 v[242:243], v[50:51], s[50:51]
	v_pk_mul_f32 v[244:245], v[34:35], s[50:51]
	v_pk_mul_f32 v[246:247], v[18:19], s[50:51]
	v_exp_f32_e32 v222, v222
	v_exp_f32_e32 v223, v223
	v_exp_f32_e32 v242, v242
	v_exp_f32_e32 v243, v243
	v_exp_f32_e32 v244, v244
	v_exp_f32_e32 v245, v245
	v_exp_f32_e32 v246, v246
	v_exp_f32_e32 v247, v247
	v_pk_add_f32 v[222:223], v[222:223], 1.0 op_sel_hi:[1,0]
	v_pk_add_f32 v[242:243], v[242:243], 1.0 op_sel_hi:[1,0]
	v_pk_add_f32 v[244:245], v[244:245], 1.0 op_sel_hi:[1,0]
	v_pk_add_f32 v[246:247], v[246:247], 1.0 op_sel_hi:[1,0]
	v_rcp_f32_e32 v222, v222
	v_rcp_f32_e32 v223, v223
	v_rcp_f32_e32 v242, v242
	v_rcp_f32_e32 v243, v243
	v_rcp_f32_e32 v244, v244
	v_rcp_f32_e32 v245, v245
	v_rcp_f32_e32 v246, v246
	v_rcp_f32_e32 v247, v247
	v_pk_mul_f32 v[114:115], v[114:115], v[222:223]
	v_pk_mul_f32 v[50:51], v[50:51], v[242:243]
	v_pk_mul_f32 v[34:35], v[34:35], v[244:245]
	v_pk_mul_f32 v[18:19], v[18:19], v[246:247]
	v_pk_mul_f32 v[114:115], v[114:115], v[110:111]
	v_pk_mul_f32 v[50:51], v[50:51], v[46:47]
	v_pk_mul_f32 v[34:35], v[34:35], v[30:31]
	v_pk_mul_f32 v[18:19], v[18:19], v[10:11]
	v_cvt_pk_bf16_f32 v113, v114, v115
	v_cvt_pk_bf16_f32 v49, v50, v51
	v_cvt_pk_bf16_f32 v33, v34, v35
	v_cvt_pk_bf16_f32 v17, v18, v19
	v_mov_b32_dpp v198, v12 row_shr:1 row_mask:0xf bank_mask:0xf bound_ctrl:1
	v_mov_b32_dpp v199, v13 row_shr:1 row_mask:0xf bank_mask:0xf bound_ctrl:1
	v_mov_b32_dpp v214, v4 row_shr:1 row_mask:0xf bank_mask:0xf bound_ctrl:1
	v_mov_b32_dpp v215, v5 row_shr:1 row_mask:0xf bank_mask:0xf bound_ctrl:1
	v_mov_b32_dpp v212, v24 row_shr:1 row_mask:0xf bank_mask:0xf bound_ctrl:1
	v_mov_b32_dpp v213, v25 row_shr:1 row_mask:0xf bank_mask:0xf bound_ctrl:1
	v_mov_b32_dpp v216, v20 row_shr:1 row_mask:0xf bank_mask:0xf bound_ctrl:1
	v_mov_b32_dpp v217, v21 row_shr:1 row_mask:0xf bank_mask:0xf bound_ctrl:1
	v_pk_fma_f32 v[12:13], v[12:13], v[84:85], v[80:81]
	v_pk_fma_f32 v[4:5], v[4:5], v[88:89], v[76:77]
	v_pk_fma_f32 v[12:13], v[24:25], v[64:65], v[12:13]
	v_pk_fma_f32 v[4:5], v[20:21], v[60:61], v[4:5]
	v_pk_fma_f32 v[12:13], v[40:41], v[56:57], v[12:13]
	v_pk_fma_f32 v[4:5], v[36:37], v[52:53], v[4:5]
	v_pk_fma_f32 v[24:25], v[24:25], v[84:85], v[80:81]
	v_pk_fma_f32 v[20:21], v[20:21], v[88:89], v[76:77]
	v_pk_fma_f32 v[24:25], v[40:41], v[64:65], v[24:25]
	v_pk_fma_f32 v[20:21], v[36:37], v[60:61], v[20:21]
	v_pk_fma_f32 v[24:25], v[72:73], v[56:57], v[24:25]
	v_pk_fma_f32 v[20:21], v[68:69], v[52:53], v[20:21]
	v_pk_fma_f32 v[40:41], v[40:41], v[84:85], v[80:81]
	v_pk_fma_f32 v[36:37], v[36:37], v[88:89], v[76:77]
	v_pk_fma_f32 v[40:41], v[72:73], v[64:65], v[40:41]
	v_pk_fma_f32 v[36:37], v[68:69], v[60:61], v[36:37]
	v_pk_fma_f32 v[40:41], v[198:199], v[56:57], v[40:41]
	v_pk_fma_f32 v[36:37], v[214:215], v[52:53], v[36:37]
	v_pk_fma_f32 v[72:73], v[72:73], v[84:85], v[80:81]
	v_pk_fma_f32 v[68:69], v[68:69], v[88:89], v[76:77]
	v_pk_fma_f32 v[72:73], v[198:199], v[64:65], v[72:73]
	v_pk_fma_f32 v[68:69], v[214:215], v[60:61], v[68:69]
	v_pk_fma_f32 v[72:73], v[212:213], v[56:57], v[72:73]
	v_pk_fma_f32 v[68:69], v[216:217], v[52:53], v[68:69]
	v_pk_mul_f32 v[222:223], v[72:73], s[50:51]
	v_pk_mul_f32 v[242:243], v[40:41], s[50:51]
	v_pk_mul_f32 v[244:245], v[24:25], s[50:51]
	v_pk_mul_f32 v[246:247], v[12:13], s[50:51]
	v_exp_f32_e32 v222, v222
	v_exp_f32_e32 v223, v223
	v_exp_f32_e32 v242, v242
	v_exp_f32_e32 v243, v243
	v_exp_f32_e32 v244, v244
	v_exp_f32_e32 v245, v245
	v_exp_f32_e32 v246, v246
	v_exp_f32_e32 v247, v247
	v_pk_add_f32 v[222:223], v[222:223], 1.0 op_sel_hi:[1,0]
	v_pk_add_f32 v[242:243], v[242:243], 1.0 op_sel_hi:[1,0]
	v_pk_add_f32 v[244:245], v[244:245], 1.0 op_sel_hi:[1,0]
	v_pk_add_f32 v[246:247], v[246:247], 1.0 op_sel_hi:[1,0]
	v_rcp_f32_e32 v222, v222
	v_rcp_f32_e32 v223, v223
	v_rcp_f32_e32 v242, v242
	v_rcp_f32_e32 v243, v243
	v_rcp_f32_e32 v244, v244
	v_rcp_f32_e32 v245, v245
	v_rcp_f32_e32 v246, v246
	v_rcp_f32_e32 v247, v247
	v_pk_mul_f32 v[72:73], v[72:73], v[222:223]
	v_pk_mul_f32 v[40:41], v[40:41], v[242:243]
	v_pk_mul_f32 v[24:25], v[24:25], v[244:245]
	v_pk_mul_f32 v[12:13], v[12:13], v[246:247]
	v_pk_mul_f32 v[72:73], v[72:73], v[68:69]
	v_pk_mul_f32 v[40:41], v[40:41], v[36:37]
	v_pk_mul_f32 v[24:25], v[24:25], v[20:21]
	v_pk_mul_f32 v[12:13], v[12:13], v[4:5]
	v_cvt_pk_bf16_f32 v114, v72, v73
	v_cvt_pk_bf16_f32 v50, v40, v41
	v_cvt_pk_bf16_f32 v34, v24, v25
	v_cvt_pk_bf16_f32 v18, v12, v13
	v_mov_b32_dpp v198, v14 row_shr:1 row_mask:0xf bank_mask:0xf bound_ctrl:1
	v_mov_b32_dpp v199, v15 row_shr:1 row_mask:0xf bank_mask:0xf bound_ctrl:1
	v_mov_b32_dpp v214, v6 row_shr:1 row_mask:0xf bank_mask:0xf bound_ctrl:1
	v_mov_b32_dpp v215, v7 row_shr:1 row_mask:0xf bank_mask:0xf bound_ctrl:1
	v_mov_b32_dpp v212, v26 row_shr:1 row_mask:0xf bank_mask:0xf bound_ctrl:1
	v_mov_b32_dpp v213, v27 row_shr:1 row_mask:0xf bank_mask:0xf bound_ctrl:1
	v_mov_b32_dpp v216, v22 row_shr:1 row_mask:0xf bank_mask:0xf bound_ctrl:1
	v_mov_b32_dpp v217, v23 row_shr:1 row_mask:0xf bank_mask:0xf bound_ctrl:1
	v_pk_fma_f32 v[14:15], v[14:15], v[86:87], v[82:83]
	v_pk_fma_f32 v[6:7], v[6:7], v[90:91], v[78:79]
	v_pk_fma_f32 v[14:15], v[26:27], v[66:67], v[14:15]
	v_pk_fma_f32 v[6:7], v[22:23], v[62:63], v[6:7]
	v_pk_fma_f32 v[14:15], v[42:43], v[58:59], v[14:15]
	v_pk_fma_f32 v[6:7], v[38:39], v[54:55], v[6:7]
	v_pk_fma_f32 v[26:27], v[26:27], v[86:87], v[82:83]
	v_pk_fma_f32 v[22:23], v[22:23], v[90:91], v[78:79]
	v_pk_fma_f32 v[26:27], v[42:43], v[66:67], v[26:27]
	v_pk_fma_f32 v[22:23], v[38:39], v[62:63], v[22:23]
	v_pk_fma_f32 v[26:27], v[74:75], v[58:59], v[26:27]
	v_pk_fma_f32 v[22:23], v[70:71], v[54:55], v[22:23]
	v_pk_fma_f32 v[42:43], v[42:43], v[86:87], v[82:83]
	v_pk_fma_f32 v[38:39], v[38:39], v[90:91], v[78:79]
	v_pk_fma_f32 v[42:43], v[74:75], v[66:67], v[42:43]
	v_pk_fma_f32 v[38:39], v[70:71], v[62:63], v[38:39]
	v_pk_fma_f32 v[42:43], v[198:199], v[58:59], v[42:43]
	v_pk_fma_f32 v[38:39], v[214:215], v[54:55], v[38:39]
	v_pk_fma_f32 v[74:75], v[74:75], v[86:87], v[82:83]
	v_pk_fma_f32 v[70:71], v[70:71], v[90:91], v[78:79]
	v_pk_fma_f32 v[74:75], v[198:199], v[66:67], v[74:75]
	v_pk_fma_f32 v[70:71], v[214:215], v[62:63], v[70:71]
	v_pk_fma_f32 v[74:75], v[212:213], v[58:59], v[74:75]
	v_pk_fma_f32 v[70:71], v[216:217], v[54:55], v[70:71]
	v_pk_mul_f32 v[222:223], v[74:75], s[50:51]
	v_pk_mul_f32 v[242:243], v[42:43], s[50:51]
	v_pk_mul_f32 v[244:245], v[26:27], s[50:51]
	v_pk_mul_f32 v[246:247], v[14:15], s[50:51]
	v_exp_f32_e32 v222, v222
	v_exp_f32_e32 v223, v223
	v_exp_f32_e32 v242, v242
	v_exp_f32_e32 v243, v243
	v_exp_f32_e32 v244, v244
	v_exp_f32_e32 v245, v245
	v_exp_f32_e32 v246, v246
	v_exp_f32_e32 v247, v247
	v_pk_add_f32 v[222:223], v[222:223], 1.0 op_sel_hi:[1,0]
	v_pk_add_f32 v[242:243], v[242:243], 1.0 op_sel_hi:[1,0]
	v_pk_add_f32 v[244:245], v[244:245], 1.0 op_sel_hi:[1,0]
	v_pk_add_f32 v[246:247], v[246:247], 1.0 op_sel_hi:[1,0]
	v_rcp_f32_e32 v222, v222
	v_rcp_f32_e32 v223, v223
	v_rcp_f32_e32 v242, v242
	v_rcp_f32_e32 v243, v243
	v_rcp_f32_e32 v244, v244
	v_rcp_f32_e32 v245, v245
	v_rcp_f32_e32 v246, v246
	v_rcp_f32_e32 v247, v247
	v_pk_mul_f32 v[74:75], v[74:75], v[222:223]
	v_pk_mul_f32 v[42:43], v[42:43], v[242:243]
	v_pk_mul_f32 v[26:27], v[26:27], v[244:245]
	v_pk_mul_f32 v[14:15], v[14:15], v[246:247]
	v_pk_mul_f32 v[74:75], v[74:75], v[70:71]
	v_pk_mul_f32 v[42:43], v[42:43], v[38:39]
	v_pk_mul_f32 v[26:27], v[26:27], v[22:23]
	v_pk_mul_f32 v[14:15], v[14:15], v[6:7]
	v_cvt_pk_bf16_f32 v115, v74, v75
	v_cvt_pk_bf16_f32 v51, v42, v43
	v_cvt_pk_bf16_f32 v35, v26, v27
	v_cvt_pk_bf16_f32 v19, v14, v15
	s_add_u32 s20, s82, 0xb0000
	s_addc_u32 s21, s83, 0
	global_store_dwordx4 v240, v[112:115], s[20:21]
	s_add_u32 s20, s82, 0xb1600
	s_addc_u32 s21, s83, 0
	global_store_dwordx4 v240, v[48:51], s[20:21]
	s_add_u32 s20, s82, 0xb2c00
	s_addc_u32 s21, s83, 0
	global_store_dwordx4 v240, v[32:35], s[20:21]
	s_add_u32 s20, s82, 0xb4200
	s_addc_u32 s21, s83, 0
	global_store_dwordx4 v240, v[16:19], s[20:21]
	s_mov_b64 s[50:51], -1
	s_branch .LBB0_76
